# grid barrier leader poll: 16 arrival counters read with all loads in flight and one wait, instead of 15 dependent load-wait rounds per pass
# baseline (speedup 1.0000x reference)
.LBB0_379:
	v_readlane_b32 s2, v247, 31
	v_readlane_b32 s3, v247, 32
	s_mov_b64 s[6:7], -1
	s_waitcnt lgkmcnt(0)
	s_nop 2
	global_load_dword v0, v193, s[2:3] sc1
	v_readlane_b32 s2, v247, 33
	v_readlane_b32 s3, v247, 34
	s_nop 4
	global_load_dword v1, v193, s[2:3] sc1
	v_readlane_b32 s2, v247, 35
	v_readlane_b32 s3, v247, 36
	s_nop 4
	global_load_dword v2, v193, s[2:3] sc1
	v_readlane_b32 s2, v247, 37
	v_readlane_b32 s3, v247, 38
	s_nop 4
	global_load_dword v3, v193, s[2:3] sc1
	v_readlane_b32 s2, v247, 39
	v_readlane_b32 s3, v247, 40
	s_nop 4
	global_load_dword v4, v193, s[2:3] sc1
	v_readlane_b32 s2, v247, 41
	v_readlane_b32 s3, v247, 42
	s_nop 4
	global_load_dword v5, v193, s[2:3] sc1
	v_readlane_b32 s2, v247, 43
	v_readlane_b32 s3, v247, 44
	s_nop 4
	global_load_dword v6, v193, s[2:3] sc1
	v_readlane_b32 s2, v247, 45
	v_readlane_b32 s3, v247, 46
	s_nop 4
	global_load_dword v7, v193, s[2:3] sc1
	v_readlane_b32 s2, v247, 47
	v_readlane_b32 s3, v247, 48
	s_nop 4
	global_load_dword v8, v193, s[2:3] sc1
	v_readlane_b32 s2, v247, 49
	v_readlane_b32 s3, v247, 50
	s_nop 4
	global_load_dword v9, v193, s[2:3] sc1
	v_readlane_b32 s2, v247, 51
	v_readlane_b32 s3, v247, 52
	s_nop 4
	global_load_dword v10, v193, s[2:3] sc1
	v_readlane_b32 s2, v247, 53
	v_readlane_b32 s3, v247, 54
	s_nop 4
	global_load_dword v11, v193, s[2:3] sc1
	v_readlane_b32 s2, v247, 55
	v_readlane_b32 s3, v247, 56
	s_nop 4
	global_load_dword v12, v193, s[2:3] sc1
	v_readlane_b32 s2, v247, 57
	v_readlane_b32 s3, v247, 58
	s_nop 4
	global_load_dword v13, v193, s[2:3] sc1
	v_readlane_b32 s2, v247, 59
	v_readlane_b32 s3, v247, 60
	s_nop 4
	global_load_dword v14, v193, s[2:3] sc1
	v_readlane_b32 s2, v247, 61
	v_readlane_b32 s3, v247, 62
	s_nop 4
	global_load_dword v15, v193, s[2:3] sc1
	s_mov_b64 s[2:3], -1
	s_waitcnt vmcnt(0)
	v_add_u32_e32 v16, v1, v0
	v_add_u32_e32 v16, v16, v2
	v_add_u32_e32 v16, v16, v3
	v_add_u32_e32 v16, v16, v4
	v_add_u32_e32 v16, v16, v5
	v_add_u32_e32 v16, v16, v6
	v_add_u32_e32 v16, v16, v7
	v_add_u32_e32 v16, v16, v8
	v_add_u32_e32 v16, v16, v9
	v_add_u32_e32 v16, v16, v10
	v_add_u32_e32 v16, v16, v11
	v_add_u32_e32 v16, v16, v12
	v_add_u32_e32 v16, v16, v13
	v_add_u32_e32 v16, v16, v14
	v_add_u32_e32 v16, v16, v15
	v_cmp_eq_u32_e32 vcc, s68, v16
	s_cbranch_vccnz .LBB0_378
	s_and_b32 s2, s5, 0xff
	s_cmp_eq_u32 s2, 0
	s_mov_b64 s[2:3], -1
	s_mov_b64 s[8:9], -1
	s_sleep 1
	s_cbranch_scc0 .LBB0_383
	global_load_dword v16, v193, s[30:31] sc1
	s_waitcnt vmcnt(0)
	v_cmp_eq_u32_e32 vcc, 0, v16
	s_cbranch_vccnz .LBB0_385
	s_mov_b64 s[8:9], 0
